# static s_setprio 1 for waves 4-7 during the FoX attention block loop (reset at phase exit); on union stack
# speedup vs baseline: 1.0064x; 1.0064x over previous
; __device__ __forceinline__ fox::BlockRef fox_item(int L) { return fox_ref(L & 31, 15 - (L >> 5)); }
; __device__ __forceinline__ void p5_fox(Frame& F, char* lds) {
;     constexpr int TOTAL = BATCH * NH * (SEQ / 256);
;     __syncthreads();
;     if (F.tid == 0) { const unsigned a_ = __hip_atomic_fetch_add(F.ctl + CW_QUEUE, 1u, RLX_AGENT), b_ = __hip_atomic_fetch_add(F.ctl + CW_QUEUE, 1u, RLX_AGENT); F.MISC[16] = a_; F.MISC[17] = b_; }
;     __syncthreads();
;     int cur = (int)F.MISC[16]; if (cur >= TOTAL) return;
;     int nxt = (int)F.MISC[17];
;     const fox::Bases Bs{(const bf16*)(F.ws + WS_P), (const bf16*)(F.ws + WS_KX), (bf16*)(F.ws + WS_MIX)};
;     fox::Seam S;
;     { const fox::BlockRef c0 = fox_item(cur); fox::fox_prime<NPP, LDMIX>(Bs, c0, lds, S); }
.LBB0_1437:
	s_waitcnt vmcnt(0) lgkmcnt(0)
	s_barrier
	v_readfirstlane_b32 s98, v0
	s_cmpk_lt_u32 s98, 0x100
	s_cbranch_scc1 .Lfox_prio_skip
	s_setprio 1
.Lfox_prio_skip:
	v_mbcnt_lo_u32_b32 v4, -1, 0
	v_mbcnt_hi_u32_b32 v4, -1, v4
	v_readfirstlane_b32 s40, v0
	s_lshr_b32 s40, s40, 6
	v_readlane_b32 s42, v252, 14
	v_readlane_b32 s43, v252, 15
	v_readlane_b32 s44, v252, 16
	v_readlane_b32 s45, v252, 17
	v_lshlrev_b32_e32 v5, 2, v4
	s_nop 4
	s_add_u32 s46, s82, 0x500000
	s_addc_u32 s47, s83, 0
	v_lshlrev_b32_e32 v24, 6, v4
	v_add_u32_e32 v24, -1, v24
	v_max_i32_e32 v24, 0, v24
	v_lshlrev_b32_e32 v24, 4, v24
	s_lshl_b32 s48, s40, 18
	s_add_u32 s64, s46, s48
	s_addc_u32 s65, s47, 0
	s_add_u32 s66, s64, 0x10000
	s_addc_u32 s67, s65, 0
	s_add_u32 s68, s64, 0x20000
	s_addc_u32 s69, s65, 0
	s_add_u32 s70, s64, 0x30000
	s_addc_u32 s71, s65, 0
	global_load_dwordx2 v[16:17], v24, s[64:65]
	global_load_dwordx2 v[18:19], v24, s[66:67]
	global_load_dwordx2 v[20:21], v24, s[68:69]
	global_load_dwordx2 v[22:23], v24, s[70:71]
	global_load_dword v6, v5, s[42:43]
	global_load_dword v7, v5, s[42:43] offset:256
	global_load_dword v8, v5, s[44:45]
	global_load_dword v9, v5, s[44:45] offset:256
	s_waitcnt vmcnt(0)
	v_and_b32_e32 v6, 0x7fffffff, v6
	v_and_b32_e32 v7, 0x7fffffff, v7
	v_and_b32_e32 v8, 0x7fffffff, v8
	v_and_b32_e32 v9, 0x7fffffff, v9
	v_max_u32_e32 v6, v6, v7
	v_max_u32_e32 v8, v8, v9
	v_xor_b32_e32 v10, 4, v5
	ds_bpermute_b32 v11, v10, v6
	ds_bpermute_b32 v12, v10, v8
	s_waitcnt lgkmcnt(0)
	v_max_u32_e32 v6, v6, v11
	v_max_u32_e32 v8, v8, v12
	v_xor_b32_e32 v10, 8, v5
	ds_bpermute_b32 v11, v10, v6
	ds_bpermute_b32 v12, v10, v8
	s_waitcnt lgkmcnt(0)
	v_max_u32_e32 v6, v6, v11
	v_max_u32_e32 v8, v8, v12
	v_xor_b32_e32 v10, 16, v5
	ds_bpermute_b32 v11, v10, v6
	ds_bpermute_b32 v12, v10, v8
	s_waitcnt lgkmcnt(0)
	v_max_u32_e32 v6, v6, v11
	v_max_u32_e32 v8, v8, v12
	v_xor_b32_e32 v10, 32, v5
	ds_bpermute_b32 v11, v10, v6
	ds_bpermute_b32 v12, v10, v8
	s_waitcnt lgkmcnt(0)
	v_max_u32_e32 v6, v6, v11
	v_max_u32_e32 v8, v8, v12
	v_xor_b32_e32 v10, 64, v5
	ds_bpermute_b32 v11, v10, v6
	ds_bpermute_b32 v12, v10, v8
	s_waitcnt lgkmcnt(0)
	v_max_u32_e32 v6, v6, v11
	v_max_u32_e32 v8, v8, v12
	v_xor_b32_e32 v10, 128, v5
	ds_bpermute_b32 v11, v10, v6
	ds_bpermute_b32 v12, v10, v8
	s_waitcnt lgkmcnt(0)
	v_max_u32_e32 v6, v6, v11
	v_max_u32_e32 v8, v8, v12
	v_mul_f32_e32 v6, v6, v8
	v_mov_b32_e32 v7, 0x41b80000
	v_mov_b32_e32 v8, 0x42e20000
	v_fma_f32 v6, v6, v7, v8
	v_mul_f32_e32 v6, 0x41351eb8, v6
	s_lshl_b32 s48, s40, 2
	s_mov_b32 s49, 0

; __device__ __forceinline__ unsigned xb_ld(unsigned* p)              { return __hip_atomic_load(p, __ATOMIC_RELAXED, __HIP_MEMORY_SCOPE_AGENT); }
; __device__ __forceinline__ void xcd_barrier_complete(unsigned* bar, unsigned x, unsigned& nloc, unsigned& nx) {
;     const unsigned G = gridDim.x * gridDim.y * gridDim.z;
;     unsigned sum, cnt, mine, sp = 0u;
;     for (;;) {
;         sum = 0u; cnt = 0u; mine = 0u;
; #pragma unroll
;         for (unsigned j = 0; j < 16; ++j) { const unsigned c = xb_ld(&bar[XB_XCNT(j)]); sum += c; cnt += (c > 0u) ? 1u : 0u; mine = (j == x) ? c : mine; }
;         if (sum == G) break;
; __device__ __forceinline__ void xcd_barrier(const XcdBarrier& b) {
;     asm volatile("s_waitcnt vmcnt(0)" ::: "memory");
;     __syncthreads();
;     if (threadIdx.x == 0) {
;         unsigned* bar = b.bar;
;         __builtin_amdgcn_s_waitcnt(0);
;         unsigned nloc = b.st[0], nx = b.st[1];
;         if (nloc == 0u) { xcd_barrier_complete(bar, b.x, nloc, nx); b.st[0] = nloc; b.st[1] = nx; }
.LBB0_1631:
	s_setprio 0
	s_cmp_lt_i32 s87, 8
	v_readlane_b32 s95, v252, 51
	v_readlane_b32 s88, v252, 40
	v_readlane_b32 s89, v252, 41
	s_cbranch_scc1 .LBB0_1681
	s_waitcnt vmcnt(0)
	v_cmp_eq_u32_e32 vcc, 0, v0
	s_barrier
	s_and_saveexec_b64 s[0:1], vcc
	s_cbranch_execz .LBB0_1680
	v_readlane_b32 s2, v252, 35
	s_waitcnt vmcnt(0) expcnt(0) lgkmcnt(0)
	s_nop 0
	v_mov_b32_e32 v1, s2
	ds_read_b32 v3, v1
	ds_read_b32 v1, v1 offset:4
	s_waitcnt lgkmcnt(1)
	v_cmp_ne_u32_e32 vcc, 0, v3
	s_cbranch_vccnz .LBB0_1648
	v_readlane_b32 s4, v252, 0
	v_readlane_b32 s5, v252, 1
	s_load_dwordx2 s[8:9], s[4:5], 0x4
	s_add_u32 s4, s82, 0x4200
	s_addc_u32 s5, s83, 0
	s_add_u32 s6, s82, 0x4400
	s_addc_u32 s7, s83, 0
	s_waitcnt lgkmcnt(0)
	s_mul_i32 s2, s8, s3
	s_add_u32 s8, s82, 0x4500
	s_mul_i32 s2, s2, s9
	s_addc_u32 s9, s83, 0
	s_add_u32 s10, s82, 0x4600
	s_addc_u32 s11, s83, 0
	s_add_u32 s12, s82, 0x4700
	s_addc_u32 s13, s83, 0
	s_add_u32 s14, s82, 0x4800
	s_addc_u32 s15, s83, 0
	s_add_u32 s16, s82, 0x4900
	s_addc_u32 s17, s83, 0
	s_add_u32 s18, s82, 0x4a00
	s_addc_u32 s19, s83, 0
	s_add_u32 s20, s82, 0x4b00
	s_addc_u32 s21, s83, 0
	s_add_u32 s22, s82, 0x4c00
	s_addc_u32 s23, s83, 0
	s_add_u32 s24, s82, 0x4d00
	s_addc_u32 s25, s83, 0
	s_add_u32 s26, s82, 0x4e00
	s_addc_u32 s27, s83, 0
	s_add_u32 s28, s82, 0x4f00
	s_addc_u32 s29, s83, 0
	s_add_u32 s30, s82, 0x5000
	s_addc_u32 s31, s83, 0
	s_add_u32 s34, s82, 0x5100
	s_addc_u32 s35, s83, 0
	s_add_u32 s36, s82, 0x5200
	s_addc_u32 s37, s83, 0
	s_add_u32 s38, s82, 0x5300
	s_addc_u32 s39, s83, 0
	s_mov_b32 s33, 1
	v_mov_b32_e32 v17, 0
	s_branch .LBB0_1636
